# speedup vs baseline: 1.0207x; 1.0005x over previous
; __device__ __forceinline__ float sigmoidf_(float x) { return __builtin_amdgcn_rcpf(1.0f + __expf(-x)); }
; __device__ __forceinline__ void gemm_run(const GemmDesc& g, char* shm) {
;     ...
;       case E_R1: {
;         const int slab = __builtin_amdgcn_readfirstlane(g.col0 + bcol + wc * 64);
;         u16* base = nullptr; int ld = 1024, off = 0, act = 0;
;         if (slab < 1024) { base = (u16*)g.o0; off = slab; }
;         else if (slab < 2048) { base = (u16*)g.o1; off = slab - 1024; }
;         else if (slab < 3072) { base = (u16*)g.o2; off = slab - 2048; }
;         else if (slab < 3136) { base = (u16*)g.o3; ld = 64; off = 0; act = 1; }
;         else if (slab < 3200) { base = (u16*)g.o4; ld = 64; off = 0; }
;         else if (slab < 3328) { base = (u16*)g.o5; ld = 128; off = slab - 3200; act = 2; }
;         else if (slab < 3392) { base = (u16*)g.o6; ld = 64; off = 0; }
;         if (base) {
; #pragma unroll
;           for (int m = 0; m < 8; ++m)
; #pragma unroll
;             for (int n = 0; n < 4; ++n) {
;               const int row = brow + wr * 128 + m * 16 + fr;
;               float t0 = acc[m][n][0], t1 = acc[m][n][1], t2 = acc[m][n][2], t3 = acc[m][n][3];
;               if (act == 1) { t0 = tanhf(t0); t1 = tanhf(t1); t2 = tanhf(t2); t3 = tanhf(t3); }
;               else if (act == 2) { t0 = sigmoidf_(t0); t1 = sigmoidf_(t1); t2 = sigmoidf_(t2); t3 = sigmoidf_(t3); }
;               uint2 o; o.x = pack2(t0, t1); o.y = pack2(t2, t3);
;               *(uint2*)(base + (size_t)row * ld + off + n * 16 + fq * 4) = o;
;             }
.LBB0_293:
	s_andn2_b64 vcc, exec, s[4:5]
	s_cbranch_vccnz .LBB0_295
	v_readfirstlane_b32 s6, v175
	s_mov_b64 s[62:63], s[66:67]
	s_movk_i32 s80, 0x400
	s_add_i32 s6, s6, s38
	s_branch .Lr1_fast
